# also defers the attention output-projection weight conversion to the idle workgroups
# speedup vs baseline: 1.0136x; 1.0090x over previous
.LBB0_90:
	s_andn2_b64 vcc, exec, s[6:7]
	s_cbranch_vccnz .LBB0_94
	s_branch .LBB0_94
	s_load_dwordx2 s[12:13], s[18:19], 0xb0
	s_lshl_b32 s6, s45, 5
	s_and_b32 s6, s6, 0x7e0
	s_and_b32 s7, s46, 0x7c0
	s_lshl_b32 s14, s6, 2
	s_waitcnt lgkmcnt(0)
	s_add_u32 s12, s12, s14
	s_addc_u32 s13, s13, 0
	v_mov_b32_e32 v33, v5
	v_lshl_add_u64 v[34:35], s[12:13], 0, v[32:33]
	s_mov_b32 s12, s7
	s_mov_b32 s13, 1
	s_mov_b32 s14, 0
	s_mov_b32 s15, 32

.Ldw_begin:
	s_and_b32 s43, s2, 7
	s_lshl_b32 s31, s0, 3
	s_add_i32 s43, s43, s31
	s_lshl_b32 s43, s43, 3
	s_add_i32 s43, s43, s85
	v_lshrrev_b32_e32 v2, 3, v244
	v_and_b32_e32 v3, 7, v244
	v_lshlrev_b32_e32 v4, 13, v2
	v_lshl_add_u32 v4, v3, 4, v4
	s_lshl_b32 s31, s85, 14
	v_lshlrev_b32_e32 v5, 7, v2
	v_add_u32_e32 v5, s31, v5
	v_xor_b32_e32 v6, 0, v3
	v_lshl_add_u32 v110, v6, 4, v5
	v_xor_b32_e32 v6, 1, v3
	v_lshl_add_u32 v111, v6, 4, v5
	v_xor_b32_e32 v6, 2, v3
	v_lshl_add_u32 v112, v6, 4, v5
	v_xor_b32_e32 v6, 3, v3
	v_lshl_add_u32 v113, v6, 4, v5
	v_xor_b32_e32 v6, 4, v3
	v_lshl_add_u32 v114, v6, 4, v5
	v_xor_b32_e32 v6, 5, v3
	v_lshl_add_u32 v115, v6, 4, v5
	v_xor_b32_e32 v6, 6, v3
	v_lshl_add_u32 v116, v6, 4, v5
	v_xor_b32_e32 v6, 7, v3
	v_lshl_add_u32 v117, v6, 4, v5
	v_lshlrev_b32_e32 v7, 10, v3
	v_add_u32_e32 v7, s31, v7
	v_add_u32_e32 v8, 0, v2
	v_lshrrev_b32_e32 v9, 2, v8
	v_xor_b32_e32 v9, v9, v3
	v_and_b32_e32 v8, 3, v8
	v_lshl_add_u32 v8, v9, 2, v8
	v_lshl_add_u32 v118, v8, 2, v7
	v_add_u32_e32 v8, 8, v2
	v_lshrrev_b32_e32 v9, 2, v8
	v_xor_b32_e32 v9, v9, v3
	v_and_b32_e32 v8, 3, v8
	v_lshl_add_u32 v8, v9, 2, v8
	v_lshl_add_u32 v119, v8, 2, v7
	v_add_u32_e32 v8, 16, v2
	v_lshrrev_b32_e32 v9, 2, v8
	v_xor_b32_e32 v9, v9, v3
	v_and_b32_e32 v8, 3, v8
	v_lshl_add_u32 v8, v9, 2, v8
	v_lshl_add_u32 v120, v8, 2, v7
	v_add_u32_e32 v8, 24, v2
	v_lshrrev_b32_e32 v9, 2, v8
	v_xor_b32_e32 v9, v9, v3
	v_and_b32_e32 v8, 3, v8
	v_lshl_add_u32 v8, v9, 2, v8
	v_lshl_add_u32 v121, v8, 2, v7
	s_load_dwordx2 s[26:27], s[86:87], 0xd8
	s_load_dwordx2 s[28:29], s[86:87], 0x118
	s_mov_b32 s30, s43
	v_lshlrev_b32_e32 v74, 14, v2
	v_lshl_add_u32 v74, v3, 4, v74
	v_add_u32_e32 v75, 0x20000, v74
	v_add_u32_e32 v76, 0x40000, v74
	v_add_u32_e32 v77, 0x60000, v74
	s_waitcnt lgkmcnt(0)
	s_add_u32 s26, s26, 0x4000000
	s_addc_u32 s27, s27, 0
	s_add_u32 s28, s28, 0x8f00000
	s_addc_u32 s29, s29, 0
	s_lshr_b32 s34, s30, 6
	s_and_b32 s35, s30, 63
	s_mov_b32 s40, s30
	s_lshl_b32 s36, s34, 19
	s_lshl_b32 s37, s35, 7
	s_add_i32 s36, s36, s37
	s_add_u32 s38, s26, s36
	s_addc_u32 s39, s27, 0
	global_load_dwordx4 v[10:13], v4, s[38:39] nt
	s_add_u32 s38, s38, 0x10000
	s_addc_u32 s39, s39, 0
	global_load_dwordx4 v[14:17], v4, s[38:39] nt
	s_add_u32 s38, s38, 0x10000
	s_addc_u32 s39, s39, 0
	global_load_dwordx4 v[18:21], v4, s[38:39] nt
	s_add_u32 s38, s38, 0x10000
	s_addc_u32 s39, s39, 0
	global_load_dwordx4 v[22:25], v4, s[38:39] nt
	s_add_u32 s38, s38, 0x10000
	s_addc_u32 s39, s39, 0
	global_load_dwordx4 v[26:29], v4, s[38:39] nt
	s_add_u32 s38, s38, 0x10000
	s_addc_u32 s39, s39, 0
	global_load_dwordx4 v[30:33], v4, s[38:39] nt
	s_add_u32 s38, s38, 0x10000
	s_addc_u32 s39, s39, 0
	global_load_dwordx4 v[34:37], v4, s[38:39] nt
	s_add_u32 s38, s38, 0x10000
	s_addc_u32 s39, s39, 0
	global_load_dwordx4 v[38:41], v4, s[38:39] nt
	s_addk_i32 s30, 0x180
	s_and_b32 s30, s30, 0x1fff
	s_lshr_b32 s34, s30, 6
	s_and_b32 s35, s30, 63
	s_mov_b32 s41, s30
	s_lshl_b32 s36, s34, 19
	s_lshl_b32 s37, s35, 7
	s_add_i32 s36, s36, s37
	s_add_u32 s38, s26, s36
	s_addc_u32 s39, s27, 0
	global_load_dwordx4 v[42:45], v4, s[38:39] nt
	s_add_u32 s38, s38, 0x10000
	s_addc_u32 s39, s39, 0
	global_load_dwordx4 v[46:49], v4, s[38:39] nt
	s_add_u32 s38, s38, 0x10000
	s_addc_u32 s39, s39, 0
	global_load_dwordx4 v[50:53], v4, s[38:39] nt
	s_add_u32 s38, s38, 0x10000
	s_addc_u32 s39, s39, 0
	global_load_dwordx4 v[54:57], v4, s[38:39] nt
	s_add_u32 s38, s38, 0x10000
	s_addc_u32 s39, s39, 0
	global_load_dwordx4 v[58:61], v4, s[38:39] nt
	s_add_u32 s38, s38, 0x10000
	s_addc_u32 s39, s39, 0
	global_load_dwordx4 v[62:65], v4, s[38:39] nt
	s_add_u32 s38, s38, 0x10000
	s_addc_u32 s39, s39, 0
	global_load_dwordx4 v[66:69], v4, s[38:39] nt
	s_add_u32 s38, s38, 0x10000
	s_addc_u32 s39, s39, 0
	global_load_dwordx4 v[70:73], v4, s[38:39] nt
	s_addk_i32 s30, 0x180
	s_and_b32 s30, s30, 0x1fff
	s_waitcnt vmcnt(8)
	ds_write_b128 v110, v[10:13]
	ds_write_b128 v111, v[14:17] offset:1024
	ds_write_b128 v112, v[18:21] offset:2048
	ds_write_b128 v113, v[22:25] offset:3072
	ds_write_b128 v114, v[26:29] offset:4096
	ds_write_b128 v115, v[30:33] offset:5120
	ds_write_b128 v116, v[34:37] offset:6144
	ds_write_b128 v117, v[38:41] offset:7168
	ds_read2_b32 v[10:11], v118 offset1:32
	ds_read2_b32 v[12:13], v118 offset0:64 offset1:96
	ds_read2_b32 v[14:15], v118 offset0:128 offset1:160
	ds_read2_b32 v[16:17], v118 offset0:192 offset1:224
	ds_read2_b32 v[18:19], v119 offset1:32
	ds_read2_b32 v[20:21], v119 offset0:64 offset1:96
	ds_read2_b32 v[22:23], v119 offset0:128 offset1:160
	ds_read2_b32 v[24:25], v119 offset0:192 offset1:224
	ds_read2_b32 v[26:27], v120 offset1:32
	ds_read2_b32 v[28:29], v120 offset0:64 offset1:96
	ds_read2_b32 v[30:31], v120 offset0:128 offset1:160
	ds_read2_b32 v[32:33], v120 offset0:192 offset1:224
	ds_read2_b32 v[34:35], v121 offset1:32
	ds_read2_b32 v[36:37], v121 offset0:64 offset1:96
	ds_read2_b32 v[38:39], v121 offset0:128 offset1:160
	ds_read2_b32 v[40:41], v121 offset0:192 offset1:224
	s_lshr_b32 s34, s40, 6
	s_and_b32 s35, s40, 63
	s_lshl_b32 s36, s35, 19
	s_lshl_b32 s37, s34, 7
	s_add_i32 s36, s36, s37
	s_add_u32 s38, s28, s36
	s_addc_u32 s39, s29, 0
	s_waitcnt lgkmcnt(12)
	v_cvt_pk_bf16_f32 v78, v10, v11
	v_cvt_pk_bf16_f32 v79, v12, v13
	v_cvt_pk_bf16_f32 v80, v14, v15
	v_cvt_pk_bf16_f32 v81, v16, v17
	s_waitcnt lgkmcnt(8)
	v_cvt_pk_bf16_f32 v82, v18, v19
	v_cvt_pk_bf16_f32 v83, v20, v21
	v_cvt_pk_bf16_f32 v84, v22, v23
	v_cvt_pk_bf16_f32 v85, v24, v25
	s_waitcnt lgkmcnt(4)
	v_cvt_pk_bf16_f32 v86, v26, v27
	v_cvt_pk_bf16_f32 v87, v28, v29
	v_cvt_pk_bf16_f32 v88, v30, v31
	v_cvt_pk_bf16_f32 v89, v32, v33
	s_waitcnt lgkmcnt(0)
	v_cvt_pk_bf16_f32 v90, v34, v35
	v_cvt_pk_bf16_f32 v91, v36, v37
	v_cvt_pk_bf16_f32 v92, v38, v39
	v_cvt_pk_bf16_f32 v93, v40, v41
	global_store_dwordx4 v74, v[78:81], s[38:39]
	global_store_dwordx4 v75, v[82:85], s[38:39]
	global_store_dwordx4 v76, v[86:89], s[38:39]
	global_store_dwordx4 v77, v[90:93], s[38:39]
	s_lshr_b32 s34, s30, 6
	s_and_b32 s35, s30, 63
	s_mov_b32 s40, s30
	s_lshl_b32 s36, s34, 19
	s_lshl_b32 s37, s35, 7
	s_add_i32 s36, s36, s37
	s_add_u32 s38, s26, s36
	s_addc_u32 s39, s27, 0
	global_load_dwordx4 v[10:13], v4, s[38:39] nt
	s_add_u32 s38, s38, 0x10000
	s_addc_u32 s39, s39, 0
	global_load_dwordx4 v[14:17], v4, s[38:39] nt
	s_add_u32 s38, s38, 0x10000
	s_addc_u32 s39, s39, 0
	global_load_dwordx4 v[18:21], v4, s[38:39] nt
	s_add_u32 s38, s38, 0x10000
	s_addc_u32 s39, s39, 0
	global_load_dwordx4 v[22:25], v4, s[38:39] nt
	s_add_u32 s38, s38, 0x10000
	s_addc_u32 s39, s39, 0
	global_load_dwordx4 v[26:29], v4, s[38:39] nt
	s_add_u32 s38, s38, 0x10000
	s_addc_u32 s39, s39, 0
	global_load_dwordx4 v[30:33], v4, s[38:39] nt
	s_add_u32 s38, s38, 0x10000
	s_addc_u32 s39, s39, 0
	global_load_dwordx4 v[34:37], v4, s[38:39] nt
	s_add_u32 s38, s38, 0x10000
	s_addc_u32 s39, s39, 0
	global_load_dwordx4 v[38:41], v4, s[38:39] nt
	s_addk_i32 s30, 0x180
	s_and_b32 s30, s30, 0x1fff
	s_mov_b32 s42, 10
.Ldw_w2_loop:
	s_waitcnt vmcnt(12)
	ds_write_b128 v110, v[42:45]
	ds_write_b128 v111, v[46:49] offset:1024
	ds_write_b128 v112, v[50:53] offset:2048
	ds_write_b128 v113, v[54:57] offset:3072
	ds_write_b128 v114, v[58:61] offset:4096
	ds_write_b128 v115, v[62:65] offset:5120
	ds_write_b128 v116, v[66:69] offset:6144
	ds_write_b128 v117, v[70:73] offset:7168
	ds_read2_b32 v[42:43], v118 offset1:32
	ds_read2_b32 v[44:45], v118 offset0:64 offset1:96
	ds_read2_b32 v[46:47], v118 offset0:128 offset1:160
	ds_read2_b32 v[48:49], v118 offset0:192 offset1:224
	ds_read2_b32 v[50:51], v119 offset1:32
	ds_read2_b32 v[52:53], v119 offset0:64 offset1:96
	ds_read2_b32 v[54:55], v119 offset0:128 offset1:160
	ds_read2_b32 v[56:57], v119 offset0:192 offset1:224
	ds_read2_b32 v[58:59], v120 offset1:32
	ds_read2_b32 v[60:61], v120 offset0:64 offset1:96
	ds_read2_b32 v[62:63], v120 offset0:128 offset1:160
	ds_read2_b32 v[64:65], v120 offset0:192 offset1:224
	ds_read2_b32 v[66:67], v121 offset1:32
	ds_read2_b32 v[68:69], v121 offset0:64 offset1:96
	ds_read2_b32 v[70:71], v121 offset0:128 offset1:160
	ds_read2_b32 v[72:73], v121 offset0:192 offset1:224
	s_lshr_b32 s34, s41, 6
	s_and_b32 s35, s41, 63
	s_lshl_b32 s36, s35, 19
	s_lshl_b32 s37, s34, 7
	s_add_i32 s36, s36, s37
	s_add_u32 s38, s28, s36
	s_addc_u32 s39, s29, 0
	s_waitcnt lgkmcnt(12)
	v_cvt_pk_bf16_f32 v94, v42, v43
	v_cvt_pk_bf16_f32 v95, v44, v45
	v_cvt_pk_bf16_f32 v96, v46, v47
	v_cvt_pk_bf16_f32 v97, v48, v49
	s_waitcnt lgkmcnt(8)
	v_cvt_pk_bf16_f32 v98, v50, v51
	v_cvt_pk_bf16_f32 v99, v52, v53
	v_cvt_pk_bf16_f32 v100, v54, v55
	v_cvt_pk_bf16_f32 v101, v56, v57
	s_waitcnt lgkmcnt(4)
	v_cvt_pk_bf16_f32 v102, v58, v59
	v_cvt_pk_bf16_f32 v103, v60, v61
	v_cvt_pk_bf16_f32 v104, v62, v63
	v_cvt_pk_bf16_f32 v105, v64, v65
	s_waitcnt lgkmcnt(0)
	v_cvt_pk_bf16_f32 v106, v66, v67
	v_cvt_pk_bf16_f32 v107, v68, v69
	v_cvt_pk_bf16_f32 v108, v70, v71
	v_cvt_pk_bf16_f32 v109, v72, v73
	global_store_dwordx4 v74, v[94:97], s[38:39]
	global_store_dwordx4 v75, v[98:101], s[38:39]
	global_store_dwordx4 v76, v[102:105], s[38:39]
	global_store_dwordx4 v77, v[106:109], s[38:39]
	s_lshr_b32 s34, s30, 6
	s_and_b32 s35, s30, 63
	s_mov_b32 s41, s30
	s_lshl_b32 s36, s34, 19
	s_lshl_b32 s37, s35, 7
	s_add_i32 s36, s36, s37
	s_add_u32 s38, s26, s36
	s_addc_u32 s39, s27, 0
	global_load_dwordx4 v[42:45], v4, s[38:39] nt
	s_add_u32 s38, s38, 0x10000
	s_addc_u32 s39, s39, 0
	global_load_dwordx4 v[46:49], v4, s[38:39] nt
	s_add_u32 s38, s38, 0x10000
	s_addc_u32 s39, s39, 0
	global_load_dwordx4 v[50:53], v4, s[38:39] nt
	s_add_u32 s38, s38, 0x10000
	s_addc_u32 s39, s39, 0
	global_load_dwordx4 v[54:57], v4, s[38:39] nt
	s_add_u32 s38, s38, 0x10000
	s_addc_u32 s39, s39, 0
	global_load_dwordx4 v[58:61], v4, s[38:39] nt
	s_add_u32 s38, s38, 0x10000
	s_addc_u32 s39, s39, 0
	global_load_dwordx4 v[62:65], v4, s[38:39] nt
	s_add_u32 s38, s38, 0x10000
	s_addc_u32 s39, s39, 0
	global_load_dwordx4 v[66:69], v4, s[38:39] nt
	s_add_u32 s38, s38, 0x10000
	s_addc_u32 s39, s39, 0
	global_load_dwordx4 v[70:73], v4, s[38:39] nt
	s_addk_i32 s30, 0x180
	s_and_b32 s30, s30, 0x1fff
	s_waitcnt vmcnt(12)
	ds_write_b128 v110, v[10:13]
	ds_write_b128 v111, v[14:17] offset:1024
	ds_write_b128 v112, v[18:21] offset:2048
	ds_write_b128 v113, v[22:25] offset:3072
	ds_write_b128 v114, v[26:29] offset:4096
	ds_write_b128 v115, v[30:33] offset:5120
	ds_write_b128 v116, v[34:37] offset:6144
	ds_write_b128 v117, v[38:41] offset:7168
	ds_read2_b32 v[10:11], v118 offset1:32
	ds_read2_b32 v[12:13], v118 offset0:64 offset1:96
	ds_read2_b32 v[14:15], v118 offset0:128 offset1:160
	ds_read2_b32 v[16:17], v118 offset0:192 offset1:224
	ds_read2_b32 v[18:19], v119 offset1:32
	ds_read2_b32 v[20:21], v119 offset0:64 offset1:96
	ds_read2_b32 v[22:23], v119 offset0:128 offset1:160
	ds_read2_b32 v[24:25], v119 offset0:192 offset1:224
	ds_read2_b32 v[26:27], v120 offset1:32
	ds_read2_b32 v[28:29], v120 offset0:64 offset1:96
	ds_read2_b32 v[30:31], v120 offset0:128 offset1:160
	ds_read2_b32 v[32:33], v120 offset0:192 offset1:224
	ds_read2_b32 v[34:35], v121 offset1:32
	ds_read2_b32 v[36:37], v121 offset0:64 offset1:96
	ds_read2_b32 v[38:39], v121 offset0:128 offset1:160
	ds_read2_b32 v[40:41], v121 offset0:192 offset1:224
	s_lshr_b32 s34, s40, 6
	s_and_b32 s35, s40, 63
	s_lshl_b32 s36, s35, 19
	s_lshl_b32 s37, s34, 7
	s_add_i32 s36, s36, s37
	s_add_u32 s38, s28, s36
	s_addc_u32 s39, s29, 0
	s_waitcnt lgkmcnt(12)
	v_cvt_pk_bf16_f32 v78, v10, v11
	v_cvt_pk_bf16_f32 v79, v12, v13
	v_cvt_pk_bf16_f32 v80, v14, v15
	v_cvt_pk_bf16_f32 v81, v16, v17
	s_waitcnt lgkmcnt(8)
	v_cvt_pk_bf16_f32 v82, v18, v19
	v_cvt_pk_bf16_f32 v83, v20, v21
	v_cvt_pk_bf16_f32 v84, v22, v23
	v_cvt_pk_bf16_f32 v85, v24, v25
	s_waitcnt lgkmcnt(4)
	v_cvt_pk_bf16_f32 v86, v26, v27
	v_cvt_pk_bf16_f32 v87, v28, v29
	v_cvt_pk_bf16_f32 v88, v30, v31
	v_cvt_pk_bf16_f32 v89, v32, v33
	s_waitcnt lgkmcnt(0)
	v_cvt_pk_bf16_f32 v90, v34, v35
	v_cvt_pk_bf16_f32 v91, v36, v37
	v_cvt_pk_bf16_f32 v92, v38, v39
	v_cvt_pk_bf16_f32 v93, v40, v41
	global_store_dwordx4 v74, v[78:81], s[38:39]
	global_store_dwordx4 v75, v[82:85], s[38:39]
	global_store_dwordx4 v76, v[86:89], s[38:39]
	global_store_dwordx4 v77, v[90:93], s[38:39]
	s_lshr_b32 s34, s30, 6
	s_and_b32 s35, s30, 63
	s_mov_b32 s40, s30
	s_lshl_b32 s36, s34, 19
	s_lshl_b32 s37, s35, 7
	s_add_i32 s36, s36, s37
	s_add_u32 s38, s26, s36
	s_addc_u32 s39, s27, 0
	global_load_dwordx4 v[10:13], v4, s[38:39] nt
	s_add_u32 s38, s38, 0x10000
	s_addc_u32 s39, s39, 0
	global_load_dwordx4 v[14:17], v4, s[38:39] nt
	s_add_u32 s38, s38, 0x10000
	s_addc_u32 s39, s39, 0
	global_load_dwordx4 v[18:21], v4, s[38:39] nt
	s_add_u32 s38, s38, 0x10000
	s_addc_u32 s39, s39, 0
	global_load_dwordx4 v[22:25], v4, s[38:39] nt
	s_add_u32 s38, s38, 0x10000
	s_addc_u32 s39, s39, 0
	global_load_dwordx4 v[26:29], v4, s[38:39] nt
	s_add_u32 s38, s38, 0x10000
	s_addc_u32 s39, s39, 0
	global_load_dwordx4 v[30:33], v4, s[38:39] nt
	s_add_u32 s38, s38, 0x10000
	s_addc_u32 s39, s39, 0
	global_load_dwordx4 v[34:37], v4, s[38:39] nt
	s_add_u32 s38, s38, 0x10000
	s_addc_u32 s39, s39, 0
	global_load_dwordx4 v[38:41], v4, s[38:39] nt
	s_addk_i32 s30, 0x180
	s_and_b32 s30, s30, 0x1fff
	s_add_i32 s42, s42, -1
	s_cmp_lg_u32 s42, 0
	s_cbranch_scc1 .Ldw_w2_loop
	s_waitcnt vmcnt(12)
	ds_write_b128 v110, v[42:45]
	ds_write_b128 v111, v[46:49] offset:1024
	ds_write_b128 v112, v[50:53] offset:2048
	ds_write_b128 v113, v[54:57] offset:3072
	ds_write_b128 v114, v[58:61] offset:4096
	ds_write_b128 v115, v[62:65] offset:5120
	ds_write_b128 v116, v[66:69] offset:6144
	ds_write_b128 v117, v[70:73] offset:7168
	ds_read2_b32 v[42:43], v118 offset1:32
	ds_read2_b32 v[44:45], v118 offset0:64 offset1:96
	ds_read2_b32 v[46:47], v118 offset0:128 offset1:160
	ds_read2_b32 v[48:49], v118 offset0:192 offset1:224
	ds_read2_b32 v[50:51], v119 offset1:32
	ds_read2_b32 v[52:53], v119 offset0:64 offset1:96
	ds_read2_b32 v[54:55], v119 offset0:128 offset1:160
	ds_read2_b32 v[56:57], v119 offset0:192 offset1:224
	ds_read2_b32 v[58:59], v120 offset1:32
	ds_read2_b32 v[60:61], v120 offset0:64 offset1:96
	ds_read2_b32 v[62:63], v120 offset0:128 offset1:160
	ds_read2_b32 v[64:65], v120 offset0:192 offset1:224
	ds_read2_b32 v[66:67], v121 offset1:32
	ds_read2_b32 v[68:69], v121 offset0:64 offset1:96
	ds_read2_b32 v[70:71], v121 offset0:128 offset1:160
	ds_read2_b32 v[72:73], v121 offset0:192 offset1:224
	s_lshr_b32 s34, s41, 6
	s_and_b32 s35, s41, 63
	s_lshl_b32 s36, s35, 19
	s_lshl_b32 s37, s34, 7
	s_add_i32 s36, s36, s37
	s_add_u32 s38, s28, s36
	s_addc_u32 s39, s29, 0
	s_waitcnt lgkmcnt(12)
	v_cvt_pk_bf16_f32 v94, v42, v43
	v_cvt_pk_bf16_f32 v95, v44, v45
	v_cvt_pk_bf16_f32 v96, v46, v47
	v_cvt_pk_bf16_f32 v97, v48, v49
	s_waitcnt lgkmcnt(8)
	v_cvt_pk_bf16_f32 v98, v50, v51
	v_cvt_pk_bf16_f32 v99, v52, v53
	v_cvt_pk_bf16_f32 v100, v54, v55
	v_cvt_pk_bf16_f32 v101, v56, v57
	s_waitcnt lgkmcnt(4)
	v_cvt_pk_bf16_f32 v102, v58, v59
	v_cvt_pk_bf16_f32 v103, v60, v61
	v_cvt_pk_bf16_f32 v104, v62, v63
	v_cvt_pk_bf16_f32 v105, v64, v65
	s_waitcnt lgkmcnt(0)
	v_cvt_pk_bf16_f32 v106, v66, v67
	v_cvt_pk_bf16_f32 v107, v68, v69
	v_cvt_pk_bf16_f32 v108, v70, v71
	v_cvt_pk_bf16_f32 v109, v72, v73
	global_store_dwordx4 v74, v[94:97], s[38:39]
	global_store_dwordx4 v75, v[98:101], s[38:39]
	global_store_dwordx4 v76, v[102:105], s[38:39]
	global_store_dwordx4 v77, v[106:109], s[38:39]
	s_waitcnt vmcnt(0) lgkmcnt(0)
	s_load_dwordx2 s[26:27], s[86:87], 0xb0
	s_load_dwordx2 s[28:29], s[86:87], 0x118
	s_mov_b32 s30, s43
	v_lshlrev_b32_e32 v74, 12, v2
	v_lshl_add_u32 v74, v3, 4, v74
	v_add_u32_e32 v75, 0x8000, v74
	v_add_u32_e32 v76, 0x10000, v74
	v_add_u32_e32 v77, 0x18000, v74
	s_waitcnt lgkmcnt(0)
	s_add_u32 s28, s28, 0x6700000
	s_addc_u32 s29, s29, 0
	s_lshr_b32 s34, s30, 6
	s_and_b32 s35, s30, 63
	s_mov_b32 s40, s30
	s_lshl_b32 s36, s34, 19
	s_lshl_b32 s37, s35, 7
	s_add_i32 s36, s36, s37
	s_add_u32 s38, s26, s36
	s_addc_u32 s39, s27, 0
	global_load_dwordx4 v[10:13], v4, s[38:39] nt
	s_add_u32 s38, s38, 0x10000
	s_addc_u32 s39, s39, 0
	global_load_dwordx4 v[14:17], v4, s[38:39] nt
	s_add_u32 s38, s38, 0x10000
	s_addc_u32 s39, s39, 0
	global_load_dwordx4 v[18:21], v4, s[38:39] nt
	s_add_u32 s38, s38, 0x10000
	s_addc_u32 s39, s39, 0
	global_load_dwordx4 v[22:25], v4, s[38:39] nt
	s_add_u32 s38, s38, 0x10000
	s_addc_u32 s39, s39, 0
	global_load_dwordx4 v[26:29], v4, s[38:39] nt
	s_add_u32 s38, s38, 0x10000
	s_addc_u32 s39, s39, 0
	global_load_dwordx4 v[30:33], v4, s[38:39] nt
	s_add_u32 s38, s38, 0x10000
	s_addc_u32 s39, s39, 0
	global_load_dwordx4 v[34:37], v4, s[38:39] nt
	s_add_u32 s38, s38, 0x10000
	s_addc_u32 s39, s39, 0
	global_load_dwordx4 v[38:41], v4, s[38:39] nt
	s_addk_i32 s30, 0x180
	s_and_b32 s30, s30, 0x7ff
	s_lshr_b32 s34, s30, 6
	s_and_b32 s35, s30, 63
	s_mov_b32 s41, s30
	s_lshl_b32 s36, s34, 19
	s_lshl_b32 s37, s35, 7
	s_add_i32 s36, s36, s37
	s_add_u32 s38, s26, s36
	s_addc_u32 s39, s27, 0
	global_load_dwordx4 v[42:45], v4, s[38:39] nt
	s_add_u32 s38, s38, 0x10000
	s_addc_u32 s39, s39, 0
	global_load_dwordx4 v[46:49], v4, s[38:39] nt
	s_add_u32 s38, s38, 0x10000
	s_addc_u32 s39, s39, 0
	global_load_dwordx4 v[50:53], v4, s[38:39] nt
	s_add_u32 s38, s38, 0x10000
	s_addc_u32 s39, s39, 0
	global_load_dwordx4 v[54:57], v4, s[38:39] nt
	s_add_u32 s38, s38, 0x10000
	s_addc_u32 s39, s39, 0
	global_load_dwordx4 v[58:61], v4, s[38:39] nt
	s_add_u32 s38, s38, 0x10000
	s_addc_u32 s39, s39, 0
	global_load_dwordx4 v[62:65], v4, s[38:39] nt
	s_add_u32 s38, s38, 0x10000
	s_addc_u32 s39, s39, 0
	global_load_dwordx4 v[66:69], v4, s[38:39] nt
	s_add_u32 s38, s38, 0x10000
	s_addc_u32 s39, s39, 0
	global_load_dwordx4 v[70:73], v4, s[38:39] nt
	s_addk_i32 s30, 0x180
	s_and_b32 s30, s30, 0x7ff
	s_waitcnt vmcnt(8)
	ds_write_b128 v110, v[10:13]
	ds_write_b128 v111, v[14:17] offset:1024
	ds_write_b128 v112, v[18:21] offset:2048
	ds_write_b128 v113, v[22:25] offset:3072
	ds_write_b128 v114, v[26:29] offset:4096
	ds_write_b128 v115, v[30:33] offset:5120
	ds_write_b128 v116, v[34:37] offset:6144
	ds_write_b128 v117, v[38:41] offset:7168
	ds_read2_b32 v[10:11], v118 offset1:32
	ds_read2_b32 v[12:13], v118 offset0:64 offset1:96
	ds_read2_b32 v[14:15], v118 offset0:128 offset1:160
	ds_read2_b32 v[16:17], v118 offset0:192 offset1:224
	ds_read2_b32 v[18:19], v119 offset1:32
	ds_read2_b32 v[20:21], v119 offset0:64 offset1:96
	ds_read2_b32 v[22:23], v119 offset0:128 offset1:160
	ds_read2_b32 v[24:25], v119 offset0:192 offset1:224
	ds_read2_b32 v[26:27], v120 offset1:32
	ds_read2_b32 v[28:29], v120 offset0:64 offset1:96
	ds_read2_b32 v[30:31], v120 offset0:128 offset1:160
	ds_read2_b32 v[32:33], v120 offset0:192 offset1:224
	ds_read2_b32 v[34:35], v121 offset1:32
	ds_read2_b32 v[36:37], v121 offset0:64 offset1:96
	ds_read2_b32 v[38:39], v121 offset0:128 offset1:160
	ds_read2_b32 v[40:41], v121 offset0:192 offset1:224
	s_lshr_b32 s34, s40, 6
	s_and_b32 s35, s40, 63
	s_lshl_b32 s36, s35, 17
	s_lshl_b32 s37, s34, 7
	s_add_i32 s36, s36, s37
	s_add_u32 s38, s28, s36
	s_addc_u32 s39, s29, 0
	s_waitcnt lgkmcnt(12)
	v_cvt_pk_bf16_f32 v78, v10, v11
	v_cvt_pk_bf16_f32 v79, v12, v13
	v_cvt_pk_bf16_f32 v80, v14, v15
	v_cvt_pk_bf16_f32 v81, v16, v17
	s_waitcnt lgkmcnt(8)
	v_cvt_pk_bf16_f32 v82, v18, v19
	v_cvt_pk_bf16_f32 v83, v20, v21
	v_cvt_pk_bf16_f32 v84, v22, v23
	v_cvt_pk_bf16_f32 v85, v24, v25
	s_waitcnt lgkmcnt(4)
	v_cvt_pk_bf16_f32 v86, v26, v27
	v_cvt_pk_bf16_f32 v87, v28, v29
	v_cvt_pk_bf16_f32 v88, v30, v31
	v_cvt_pk_bf16_f32 v89, v32, v33
	s_waitcnt lgkmcnt(0)
	v_cvt_pk_bf16_f32 v90, v34, v35
	v_cvt_pk_bf16_f32 v91, v36, v37
	v_cvt_pk_bf16_f32 v92, v38, v39
	v_cvt_pk_bf16_f32 v93, v40, v41
	global_store_dwordx4 v74, v[78:81], s[38:39]
	global_store_dwordx4 v75, v[82:85], s[38:39]
	global_store_dwordx4 v76, v[86:89], s[38:39]
	global_store_dwordx4 v77, v[90:93], s[38:39]
	s_lshr_b32 s34, s30, 6
	s_and_b32 s35, s30, 63
	s_mov_b32 s40, s30
	s_lshl_b32 s36, s34, 19
	s_lshl_b32 s37, s35, 7
	s_add_i32 s36, s36, s37
	s_add_u32 s38, s26, s36
	s_addc_u32 s39, s27, 0
	global_load_dwordx4 v[10:13], v4, s[38:39] nt
	s_add_u32 s38, s38, 0x10000
	s_addc_u32 s39, s39, 0
	global_load_dwordx4 v[14:17], v4, s[38:39] nt
	s_add_u32 s38, s38, 0x10000
	s_addc_u32 s39, s39, 0
	global_load_dwordx4 v[18:21], v4, s[38:39] nt
	s_add_u32 s38, s38, 0x10000
	s_addc_u32 s39, s39, 0
	global_load_dwordx4 v[22:25], v4, s[38:39] nt
	s_add_u32 s38, s38, 0x10000
	s_addc_u32 s39, s39, 0
	global_load_dwordx4 v[26:29], v4, s[38:39] nt
	s_add_u32 s38, s38, 0x10000
	s_addc_u32 s39, s39, 0
	global_load_dwordx4 v[30:33], v4, s[38:39] nt
	s_add_u32 s38, s38, 0x10000
	s_addc_u32 s39, s39, 0
	global_load_dwordx4 v[34:37], v4, s[38:39] nt
	s_add_u32 s38, s38, 0x10000
	s_addc_u32 s39, s39, 0
	global_load_dwordx4 v[38:41], v4, s[38:39] nt
	s_addk_i32 s30, 0x180
	s_and_b32 s30, s30, 0x7ff
	s_mov_b32 s42, 2
.Ldw_wo_loop:
	s_waitcnt vmcnt(12)
	ds_write_b128 v110, v[42:45]
	ds_write_b128 v111, v[46:49] offset:1024
	ds_write_b128 v112, v[50:53] offset:2048
	ds_write_b128 v113, v[54:57] offset:3072
	ds_write_b128 v114, v[58:61] offset:4096
	ds_write_b128 v115, v[62:65] offset:5120
	ds_write_b128 v116, v[66:69] offset:6144
	ds_write_b128 v117, v[70:73] offset:7168
	ds_read2_b32 v[42:43], v118 offset1:32
	ds_read2_b32 v[44:45], v118 offset0:64 offset1:96
	ds_read2_b32 v[46:47], v118 offset0:128 offset1:160
	ds_read2_b32 v[48:49], v118 offset0:192 offset1:224
	ds_read2_b32 v[50:51], v119 offset1:32
	ds_read2_b32 v[52:53], v119 offset0:64 offset1:96
	ds_read2_b32 v[54:55], v119 offset0:128 offset1:160
	ds_read2_b32 v[56:57], v119 offset0:192 offset1:224
	ds_read2_b32 v[58:59], v120 offset1:32
	ds_read2_b32 v[60:61], v120 offset0:64 offset1:96
	ds_read2_b32 v[62:63], v120 offset0:128 offset1:160
	ds_read2_b32 v[64:65], v120 offset0:192 offset1:224
	ds_read2_b32 v[66:67], v121 offset1:32
	ds_read2_b32 v[68:69], v121 offset0:64 offset1:96
	ds_read2_b32 v[70:71], v121 offset0:128 offset1:160
	ds_read2_b32 v[72:73], v121 offset0:192 offset1:224
	s_lshr_b32 s34, s41, 6
	s_and_b32 s35, s41, 63
	s_lshl_b32 s36, s35, 17
	s_lshl_b32 s37, s34, 7
	s_add_i32 s36, s36, s37
	s_add_u32 s38, s28, s36
	s_addc_u32 s39, s29, 0
	s_waitcnt lgkmcnt(12)
	v_cvt_pk_bf16_f32 v94, v42, v43
	v_cvt_pk_bf16_f32 v95, v44, v45
	v_cvt_pk_bf16_f32 v96, v46, v47
	v_cvt_pk_bf16_f32 v97, v48, v49
	s_waitcnt lgkmcnt(8)
	v_cvt_pk_bf16_f32 v98, v50, v51
	v_cvt_pk_bf16_f32 v99, v52, v53
	v_cvt_pk_bf16_f32 v100, v54, v55
	v_cvt_pk_bf16_f32 v101, v56, v57
	s_waitcnt lgkmcnt(4)
	v_cvt_pk_bf16_f32 v102, v58, v59
	v_cvt_pk_bf16_f32 v103, v60, v61
	v_cvt_pk_bf16_f32 v104, v62, v63
	v_cvt_pk_bf16_f32 v105, v64, v65
	s_waitcnt lgkmcnt(0)
	v_cvt_pk_bf16_f32 v106, v66, v67
	v_cvt_pk_bf16_f32 v107, v68, v69
	v_cvt_pk_bf16_f32 v108, v70, v71
	v_cvt_pk_bf16_f32 v109, v72, v73
	global_store_dwordx4 v74, v[94:97], s[38:39]
	global_store_dwordx4 v75, v[98:101], s[38:39]
	global_store_dwordx4 v76, v[102:105], s[38:39]
	global_store_dwordx4 v77, v[106:109], s[38:39]
	s_lshr_b32 s34, s30, 6
	s_and_b32 s35, s30, 63
	s_mov_b32 s41, s30
	s_lshl_b32 s36, s34, 19
	s_lshl_b32 s37, s35, 7
	s_add_i32 s36, s36, s37
	s_add_u32 s38, s26, s36
	s_addc_u32 s39, s27, 0
	global_load_dwordx4 v[42:45], v4, s[38:39] nt
	s_add_u32 s38, s38, 0x10000
	s_addc_u32 s39, s39, 0
	global_load_dwordx4 v[46:49], v4, s[38:39] nt
	s_add_u32 s38, s38, 0x10000
	s_addc_u32 s39, s39, 0
	global_load_dwordx4 v[50:53], v4, s[38:39] nt
	s_add_u32 s38, s38, 0x10000
	s_addc_u32 s39, s39, 0
	global_load_dwordx4 v[54:57], v4, s[38:39] nt
	s_add_u32 s38, s38, 0x10000
	s_addc_u32 s39, s39, 0
	global_load_dwordx4 v[58:61], v4, s[38:39] nt
	s_add_u32 s38, s38, 0x10000
	s_addc_u32 s39, s39, 0
	global_load_dwordx4 v[62:65], v4, s[38:39] nt
	s_add_u32 s38, s38, 0x10000
	s_addc_u32 s39, s39, 0
	global_load_dwordx4 v[66:69], v4, s[38:39] nt
	s_add_u32 s38, s38, 0x10000
	s_addc_u32 s39, s39, 0
	global_load_dwordx4 v[70:73], v4, s[38:39] nt
	s_addk_i32 s30, 0x180
	s_and_b32 s30, s30, 0x7ff
	s_waitcnt vmcnt(12)
	ds_write_b128 v110, v[10:13]
	ds_write_b128 v111, v[14:17] offset:1024
	ds_write_b128 v112, v[18:21] offset:2048
	ds_write_b128 v113, v[22:25] offset:3072
	ds_write_b128 v114, v[26:29] offset:4096
	ds_write_b128 v115, v[30:33] offset:5120
	ds_write_b128 v116, v[34:37] offset:6144
	ds_write_b128 v117, v[38:41] offset:7168
	ds_read2_b32 v[10:11], v118 offset1:32
	ds_read2_b32 v[12:13], v118 offset0:64 offset1:96
	ds_read2_b32 v[14:15], v118 offset0:128 offset1:160
	ds_read2_b32 v[16:17], v118 offset0:192 offset1:224
	ds_read2_b32 v[18:19], v119 offset1:32
	ds_read2_b32 v[20:21], v119 offset0:64 offset1:96
	ds_read2_b32 v[22:23], v119 offset0:128 offset1:160
	ds_read2_b32 v[24:25], v119 offset0:192 offset1:224
	ds_read2_b32 v[26:27], v120 offset1:32
	ds_read2_b32 v[28:29], v120 offset0:64 offset1:96
	ds_read2_b32 v[30:31], v120 offset0:128 offset1:160
	ds_read2_b32 v[32:33], v120 offset0:192 offset1:224
	ds_read2_b32 v[34:35], v121 offset1:32
	ds_read2_b32 v[36:37], v121 offset0:64 offset1:96
	ds_read2_b32 v[38:39], v121 offset0:128 offset1:160
	ds_read2_b32 v[40:41], v121 offset0:192 offset1:224
	s_lshr_b32 s34, s40, 6
	s_and_b32 s35, s40, 63
	s_lshl_b32 s36, s35, 17
	s_lshl_b32 s37, s34, 7
	s_add_i32 s36, s36, s37
	s_add_u32 s38, s28, s36
	s_addc_u32 s39, s29, 0
	s_waitcnt lgkmcnt(12)
	v_cvt_pk_bf16_f32 v78, v10, v11
	v_cvt_pk_bf16_f32 v79, v12, v13
	v_cvt_pk_bf16_f32 v80, v14, v15
	v_cvt_pk_bf16_f32 v81, v16, v17
	s_waitcnt lgkmcnt(8)
	v_cvt_pk_bf16_f32 v82, v18, v19
	v_cvt_pk_bf16_f32 v83, v20, v21
	v_cvt_pk_bf16_f32 v84, v22, v23
	v_cvt_pk_bf16_f32 v85, v24, v25
	s_waitcnt lgkmcnt(4)
	v_cvt_pk_bf16_f32 v86, v26, v27
	v_cvt_pk_bf16_f32 v87, v28, v29
	v_cvt_pk_bf16_f32 v88, v30, v31
	v_cvt_pk_bf16_f32 v89, v32, v33
	s_waitcnt lgkmcnt(0)
	v_cvt_pk_bf16_f32 v90, v34, v35
	v_cvt_pk_bf16_f32 v91, v36, v37
	v_cvt_pk_bf16_f32 v92, v38, v39
	v_cvt_pk_bf16_f32 v93, v40, v41
	global_store_dwordx4 v74, v[78:81], s[38:39]
	global_store_dwordx4 v75, v[82:85], s[38:39]
	global_store_dwordx4 v76, v[86:89], s[38:39]
	global_store_dwordx4 v77, v[90:93], s[38:39]
	s_lshr_b32 s34, s30, 6
	s_and_b32 s35, s30, 63
	s_mov_b32 s40, s30
	s_lshl_b32 s36, s34, 19
	s_lshl_b32 s37, s35, 7
	s_add_i32 s36, s36, s37
	s_add_u32 s38, s26, s36
	s_addc_u32 s39, s27, 0
	global_load_dwordx4 v[10:13], v4, s[38:39] nt
	s_add_u32 s38, s38, 0x10000
	s_addc_u32 s39, s39, 0
	global_load_dwordx4 v[14:17], v4, s[38:39] nt
	s_add_u32 s38, s38, 0x10000
	s_addc_u32 s39, s39, 0
	global_load_dwordx4 v[18:21], v4, s[38:39] nt
	s_add_u32 s38, s38, 0x10000
	s_addc_u32 s39, s39, 0
	global_load_dwordx4 v[22:25], v4, s[38:39] nt
	s_add_u32 s38, s38, 0x10000
	s_addc_u32 s39, s39, 0
	global_load_dwordx4 v[26:29], v4, s[38:39] nt
	s_add_u32 s38, s38, 0x10000
	s_addc_u32 s39, s39, 0
	global_load_dwordx4 v[30:33], v4, s[38:39] nt
	s_add_u32 s38, s38, 0x10000
	s_addc_u32 s39, s39, 0
	global_load_dwordx4 v[34:37], v4, s[38:39] nt
	s_add_u32 s38, s38, 0x10000
	s_addc_u32 s39, s39, 0
	global_load_dwordx4 v[38:41], v4, s[38:39] nt
	s_addk_i32 s30, 0x180
	s_and_b32 s30, s30, 0x7ff
	s_add_i32 s42, s42, -1
	s_cmp_lg_u32 s42, 0
	s_cbranch_scc1 .Ldw_wo_loop
	s_waitcnt vmcnt(12)
	ds_write_b128 v110, v[42:45]
	ds_write_b128 v111, v[46:49] offset:1024
	ds_write_b128 v112, v[50:53] offset:2048
	ds_write_b128 v113, v[54:57] offset:3072
	ds_write_b128 v114, v[58:61] offset:4096
	ds_write_b128 v115, v[62:65] offset:5120
	ds_write_b128 v116, v[66:69] offset:6144
	ds_write_b128 v117, v[70:73] offset:7168
	ds_read2_b32 v[42:43], v118 offset1:32
	ds_read2_b32 v[44:45], v118 offset0:64 offset1:96
	ds_read2_b32 v[46:47], v118 offset0:128 offset1:160
	ds_read2_b32 v[48:49], v118 offset0:192 offset1:224
	ds_read2_b32 v[50:51], v119 offset1:32
	ds_read2_b32 v[52:53], v119 offset0:64 offset1:96
	ds_read2_b32 v[54:55], v119 offset0:128 offset1:160
	ds_read2_b32 v[56:57], v119 offset0:192 offset1:224
	ds_read2_b32 v[58:59], v120 offset1:32
	ds_read2_b32 v[60:61], v120 offset0:64 offset1:96
	ds_read2_b32 v[62:63], v120 offset0:128 offset1:160
	ds_read2_b32 v[64:65], v120 offset0:192 offset1:224
	ds_read2_b32 v[66:67], v121 offset1:32
	ds_read2_b32 v[68:69], v121 offset0:64 offset1:96
	ds_read2_b32 v[70:71], v121 offset0:128 offset1:160
	ds_read2_b32 v[72:73], v121 offset0:192 offset1:224
	s_lshr_b32 s34, s41, 6
	s_and_b32 s35, s41, 63
	s_lshl_b32 s36, s35, 17
	s_lshl_b32 s37, s34, 7
	s_add_i32 s36, s36, s37
	s_add_u32 s38, s28, s36
	s_addc_u32 s39, s29, 0
	s_waitcnt lgkmcnt(12)
	v_cvt_pk_bf16_f32 v94, v42, v43
	v_cvt_pk_bf16_f32 v95, v44, v45
	v_cvt_pk_bf16_f32 v96, v46, v47
	v_cvt_pk_bf16_f32 v97, v48, v49
	s_waitcnt lgkmcnt(8)
	v_cvt_pk_bf16_f32 v98, v50, v51
	v_cvt_pk_bf16_f32 v99, v52, v53
	v_cvt_pk_bf16_f32 v100, v54, v55
	v_cvt_pk_bf16_f32 v101, v56, v57
	s_waitcnt lgkmcnt(4)
	v_cvt_pk_bf16_f32 v102, v58, v59
	v_cvt_pk_bf16_f32 v103, v60, v61
	v_cvt_pk_bf16_f32 v104, v62, v63
	v_cvt_pk_bf16_f32 v105, v64, v65
	s_waitcnt lgkmcnt(0)
	v_cvt_pk_bf16_f32 v106, v66, v67
	v_cvt_pk_bf16_f32 v107, v68, v69
	v_cvt_pk_bf16_f32 v108, v70, v71
	v_cvt_pk_bf16_f32 v109, v72, v73
	global_store_dwordx4 v74, v[94:97], s[38:39]
	global_store_dwordx4 v75, v[98:101], s[38:39]
	global_store_dwordx4 v76, v[102:105], s[38:39]
	global_store_dwordx4 v77, v[106:109], s[38:39]
	s_waitcnt vmcnt(0) lgkmcnt(0)
	s_branch .LBB0_1389
